# P11 gate-bias loads: three of the four serialized b_i/b_f loads issued together with counted waits (on top of v8)
# baseline (speedup 1.0000x reference)
; #define LAS __attribute__((address_space(3)))
; __device__ __forceinline__ float logsigmoid_f(float x) { return fminf(x, 0.f) - log1pf(__expf(-fabsf(x))); }
; __device__ __forceinline__ void mlstm_gates_compute(LAS float* fl, const float (&gv)[4], const float* b_i, const float* b_f, int h, int tid) {
;     LAS float* igf = fl + 256, *igb = fl + 384, *cf = fl + 512, *cb = fl + 640, *tot = fl + 768, *wt = fl + 776;
;     const int lane = tid & 63, w = tid >> 6;
;     float sf = 0.f, sb = 0.f, lb = 0.f;
;     if (tid < 128) {
;         igf[tid] = gv[0] + b_i[h]; igb[tid] = gv[1] + b_i[8 + h];
;         sf = logsigmoid_f(gv[2] + b_f[h]); lb = logsigmoid_f(gv[3] + b_f[8 + h]); sb = lb;
; __device__ __forceinline__ void mlstm_passC(LAS unsigned char* lds, const bf16_t* Z, const float* G, const float* conv_w, const float* conv_b, const float* b_i, const float* b_f, ...
;     ...
;     { const u32x4* sf = (const u32x4*)(ST + (size_t)((c * 2 + 0) * 8 + h) * 16384) + tid;
; #pragma unroll
;       for (int i = 0; i < 4; ++i) cfr[i] = sf[512 * i]; }
;     if (tid < 256) nst[tid] = nstv;
.LBB0_1003:
	s_lshl_b32 s8, s8, 4
	s_or_b32 s66, s8, s25
	s_ashr_i32 s67, s66, 31
	s_lshl_b64 s[8:9], s[66:67], 15
	v_lshl_add_u64 v[8:9], v[106:107], 0, s[8:9]
	v_add_co_u32_e32 v4, vcc, 0x2000, v8
	s_nop 1
	v_addc_co_u32_e32 v5, vcc, 0, v9, vcc
	v_add_co_u32_e32 v10, vcc, 0x4000, v8
	global_load_dwordx4 v[0:3], v[8:9], off
	s_nop 0
	global_load_dwordx4 v[4:7], v[4:5], off
	v_addc_co_u32_e32 v11, vcc, 0, v9, vcc
	v_add_co_u32_e32 v12, vcc, 0x6000, v8
	s_nop 1
	v_addc_co_u32_e32 v13, vcc, 0, v9, vcc
	global_load_dwordx4 v[8:11], v[10:11], off
	s_nop 0
	global_load_dwordx4 v[12:15], v[12:13], off
	s_and_saveexec_b64 s[68:69], s[6:7]
	ds_write_b32 v97, v130
	s_or_b64 exec, exec, s[68:69]
	v_mov_b32_e32 v18, 0
	v_mov_b32_e32 v17, 0
	v_mov_b32_e32 v16, 0
	s_and_saveexec_b64 s[68:69], s[4:5]
	s_cbranch_execz .LBB0_1009
	s_lshl_b32 s8, s25, 2
	v_mov_b32_e32 v17, s8
	global_load_dword v16, v17, s[84:85]
	global_load_dword v18, v17, s[84:85] offset:32
	global_load_dword v19, v17, s[86:87]
	s_mov_b32 s8, 0xbfb8aa3b
	s_mov_b32 s9, 0x3f2aaaab
	s_mov_b32 s10, 0x3f317218
	s_mov_b32 s11, 0x7f800000
	s_mov_b32 s12, 0x33800000
	s_waitcnt vmcnt(2)
	v_add_f32_e32 v16, v129, v16
	ds_write_b32 v153, v16
	s_waitcnt vmcnt(1)
	v_add_f32_e32 v16, v128, v18
	ds_write_b32 v154, v16
	s_waitcnt vmcnt(0)
	v_add_f32_e32 v16, v127, v19
	v_min_f32_e32 v20, 0, v16
	v_mul_f32_e64 v16, |v16|, s8
	v_exp_f32_e32 v16, v16
	global_load_dword v17, v17, s[86:87] offset:32
	v_add_f32_e32 v21, 1.0, v16
	v_add_f32_e32 v18, -1.0, v21
	v_sub_f32_e32 v19, v18, v21
	v_add_f32_e32 v19, 1.0, v19
	v_sub_f32_e32 v18, v16, v18
	v_add_f32_e32 v22, v18, v19
	v_frexp_mant_f32_e32 v18, v21
	v_cmp_gt_f32_e32 vcc, s9, v18
	v_cvt_f64_f32_e32 v[18:19], v21
	v_frexp_exp_i32_f64_e32 v18, v[18:19]
	v_subbrev_co_u32_e32 v18, vcc, 0, v18, vcc
	v_sub_u32_e32 v19, 0, v18
	v_ldexp_f32 v21, v21, v19
	v_ldexp_f32 v19, v22, v19
	v_add_f32_e32 v22, -1.0, v21
	v_add_f32_e32 v23, 1.0, v22
	v_sub_f32_e32 v23, v21, v23
	v_add_f32_e32 v23, v19, v23
	v_add_f32_e32 v24, v22, v23
	v_sub_f32_e32 v22, v24, v22
	v_sub_f32_e32 v22, v23, v22
	v_add_f32_e32 v23, 1.0, v21
	v_add_f32_e32 v25, -1.0, v23
	v_sub_f32_e32 v21, v21, v25
	v_add_f32_e32 v19, v19, v21
	v_add_f32_e32 v21, v23, v19
	v_sub_f32_e32 v23, v21, v23
	v_sub_f32_e32 v19, v19, v23
	v_rcp_f32_e32 v23, v21
	v_cvt_f32_i32_e32 v18, v18
	v_cmp_neq_f32_e32 vcc, s11, v16
	v_mul_f32_e32 v25, v24, v23
	v_mul_f32_e32 v26, v21, v25
	v_fma_f32 v27, v25, v21, -v26
	v_fmac_f32_e32 v27, v25, v19
	v_add_f32_e32 v28, v26, v27
	v_sub_f32_e32 v29, v24, v28
	v_sub_f32_e32 v24, v24, v29
	v_sub_f32_e32 v26, v28, v26
	v_sub_f32_e32 v24, v24, v28
	v_add_f32_e32 v22, v22, v24
	v_sub_f32_e32 v24, v26, v27
	v_add_f32_e32 v22, v24, v22
	v_add_f32_e32 v24, v29, v22
	v_mul_f32_e32 v26, v23, v24
	v_mul_f32_e32 v27, v21, v26
	v_fma_f32 v21, v26, v21, -v27
	v_fmac_f32_e32 v21, v26, v19
	v_sub_f32_e32 v19, v29, v24
	v_add_f32_e32 v19, v22, v19
	v_add_f32_e32 v22, v27, v21
	v_sub_f32_e32 v28, v24, v22
	v_sub_f32_e32 v24, v24, v28
	v_sub_f32_e32 v27, v22, v27
	v_sub_f32_e32 v22, v24, v22
	v_add_f32_e32 v19, v19, v22
	v_sub_f32_e32 v21, v27, v21
	v_add_f32_e32 v19, v21, v19
	v_add_f32_e32 v21, v25, v26
	v_add_f32_e32 v19, v28, v19
	v_sub_f32_e32 v22, v21, v25
	v_mul_f32_e32 v19, v23, v19
	v_sub_f32_e32 v22, v26, v22
	v_add_f32_e32 v19, v22, v19
	v_mul_f32_e32 v25, 0x3f317218, v18
	v_add_f32_e32 v22, v21, v19
	v_fma_f32 v26, v18, s10, -v25
	v_mul_f32_e32 v23, v22, v22
	v_fmac_f32_e32 v26, 0xb102e308, v18
	v_sub_f32_e32 v18, v22, v21
	v_fmamk_f32 v24, v23, 0x3e9b6dac, v109
	v_sub_f32_e32 v18, v19, v18
	v_add_f32_e32 v19, v25, v26
	v_fmaak_f32 v24, v23, v24, 0x3f2aaada
	v_sub_f32_e32 v21, v19, v25
	v_ldexp_f32 v25, v22, 1
	v_mul_f32_e32 v22, v22, v23
	v_mul_f32_e32 v22, v22, v24
	v_add_f32_e32 v23, v25, v22
	v_sub_f32_e32 v24, v23, v25
	v_ldexp_f32 v18, v18, 1
	v_sub_f32_e32 v22, v22, v24
	v_add_f32_e32 v18, v18, v22
	v_add_f32_e32 v22, v23, v18
	v_sub_f32_e32 v23, v22, v23
	v_sub_f32_e32 v18, v18, v23
	v_add_f32_e32 v23, v19, v22
	v_sub_f32_e32 v24, v23, v19
	v_sub_f32_e32 v25, v23, v24
	v_sub_f32_e32 v21, v26, v21
	v_sub_f32_e32 v19, v19, v25
	v_sub_f32_e32 v22, v22, v24
	v_add_f32_e32 v19, v22, v19
	v_add_f32_e32 v22, v21, v18
	v_sub_f32_e32 v24, v22, v21
	v_sub_f32_e32 v25, v22, v24
	v_sub_f32_e32 v21, v21, v25
	v_sub_f32_e32 v18, v18, v24
	v_add_f32_e32 v19, v22, v19
	v_add_f32_e32 v18, v18, v21
	v_add_f32_e32 v21, v23, v19
	v_sub_f32_e32 v22, v21, v23
	v_sub_f32_e32 v19, v19, v22
	v_add_f32_e32 v18, v18, v19
	v_add_f32_e32 v18, v21, v18
	v_cndmask_b32_e32 v18, v236, v18, vcc
	v_cmp_ngt_f32_e32 vcc, -1.0, v16
	s_nop 1
	v_cndmask_b32_e32 v18, v237, v18, vcc
	v_cmp_neq_f32_e32 vcc, -1.0, v16
	s_nop 1
	v_cndmask_b32_e32 v18, v238, v18, vcc
	v_cmp_lt_f32_e64 vcc, |v16|, s12
	s_nop 1
	v_cndmask_b32_e32 v16, v18, v16, vcc
	s_waitcnt vmcnt(0)
; __device__ __forceinline__ float logsigmoid_f(float x) { return fminf(x, 0.f) - log1pf(__expf(-fabsf(x))); }
; __device__ __forceinline__ void mlstm_gates_compute(LAS float* fl, const float (&gv)[4], const float* b_i, const float* b_f, int h, int tid) {
;     ...
;         sf = logsigmoid_f(gv[2] + b_f[h]); lb = logsigmoid_f(gv[3] + b_f[8 + h]); sb = lb;
; #pragma unroll
;         for (int o = 1; o < 64; o <<= 1) { const float yf = __shfl_up(sf, o), yb = __shfl_up(sb, o); if (lane >= o) { sf += yf; sb += yb; } }
;         if (lane == 63) { wt[w * 2] = sf; wt[w * 2 + 1] = sb; }
	v_add_f32_e32 v18, v117, v17
	v_min_f32_e32 v17, 0, v18
	v_mul_f32_e64 v18, |v18|, s8
	v_exp_f32_e32 v18, v18
	v_sub_f32_e32 v16, v20, v16
	v_add_f32_e32 v19, 1.0, v18
	v_add_f32_e32 v20, -1.0, v19
	v_sub_f32_e32 v21, v20, v19
	v_add_f32_e32 v21, 1.0, v21
	v_sub_f32_e32 v20, v18, v20
	v_add_f32_e32 v22, v20, v21
	v_frexp_mant_f32_e32 v20, v19
	v_cmp_gt_f32_e32 vcc, s9, v20
	v_cvt_f64_f32_e32 v[20:21], v19
	v_frexp_exp_i32_f64_e32 v20, v[20:21]
	v_subbrev_co_u32_e32 v28, vcc, 0, v20, vcc
	v_sub_u32_e32 v20, 0, v28
	v_ldexp_f32 v19, v19, v20
	v_ldexp_f32 v20, v22, v20
	v_add_f32_e32 v22, -1.0, v19
	v_add_f32_e32 v21, 1.0, v22
	v_sub_f32_e32 v21, v19, v21
	v_add_f32_e32 v23, v20, v21
	v_add_f32_e32 v21, 1.0, v19
	v_add_f32_e32 v24, -1.0, v21
	v_sub_f32_e32 v19, v19, v24
	v_add_f32_e32 v19, v20, v19
	v_add_f32_e32 v29, v21, v19
	v_rcp_f32_e32 v30, v29
	v_sub_f32_e32 v20, v29, v21
	v_add_f32_e32 v21, v22, v23
	v_sub_f32_e32 v19, v19, v20
	v_mul_f32_e32 v32, v21, v30
	v_sub_f32_e32 v20, v21, v22
	v_mul_f32_e32 v22, v29, v32
	v_fma_f32 v24, v32, v29, -v22
	v_fmac_f32_e32 v24, v32, v19
	v_sub_f32_e32 v31, v23, v20
	v_add_f32_e32 v20, v22, v24
	v_sub_f32_e32 v23, v21, v20
	v_pk_add_f32 v[26:27], v[20:21], v[22:23] neg_lo:[0,1] neg_hi:[0,1]
	v_mov_b32_e32 v25, v20
	v_pk_add_f32 v[20:21], v[26:27], v[24:25] neg_lo:[0,1] neg_hi:[0,1]
	v_cmp_neq_f32_e32 vcc, s11, v18
	v_add_f32_e32 v21, v31, v21
	v_add_f32_e32 v20, v20, v21
	v_add_f32_e32 v21, v23, v20
	v_mul_f32_e32 v31, v30, v21
	v_mul_f32_e32 v22, v29, v31
	v_fma_f32 v24, v31, v29, -v22
	v_fmac_f32_e32 v24, v31, v19
	v_sub_f32_e32 v19, v23, v21
	v_add_f32_e32 v19, v20, v19
	v_add_f32_e32 v20, v22, v24
	v_sub_f32_e32 v23, v21, v20
	v_pk_add_f32 v[26:27], v[20:21], v[22:23] neg_lo:[0,1] neg_hi:[0,1]
	v_mov_b32_e32 v25, v20
	v_pk_add_f32 v[20:21], v[26:27], v[24:25] neg_lo:[0,1] neg_hi:[0,1]
	v_readlane_b32 s8, v252, 19
	v_add_f32_e32 v19, v19, v21
	v_add_f32_e32 v19, v20, v19
	v_add_f32_e32 v21, v32, v31
	v_add_f32_e32 v19, v23, v19
	v_sub_f32_e32 v20, v21, v32
	v_mul_f32_e32 v19, v30, v19
	v_sub_f32_e32 v20, v31, v20
	v_add_f32_e32 v19, v20, v19
	v_add_f32_e32 v22, v21, v19
	v_mul_f32_e32 v24, v22, v22
	v_fmamk_f32 v20, v24, 0x3e9b6dac, v109
	v_fmaak_f32 v117, v24, v20, 0x3f2aaada
	v_cvt_f32_i32_e32 v20, v28
	v_sub_f32_e32 v21, v22, v21
	v_sub_f32_e32 v19, v19, v21
	v_mul_f32_e32 v21, v22, v24
	v_pk_mul_f32 v[24:25], v[20:21], v[116:117]
	v_ldexp_f32 v23, v22, 1
	v_fma_f32 v22, v20, s10, -v24
	v_fmac_f32_e32 v22, 0xb102e308, v20
	v_pk_add_f32 v[20:21], v[24:25], v[22:23]
	v_ldexp_f32 v19, v19, 1
	v_sub_f32_e32 v23, v21, v23
	v_sub_f32_e32 v23, v25, v23
	v_add_f32_e32 v27, v19, v23
	v_mov_b32_e32 v26, v24
	v_pk_add_f32 v[24:25], v[20:21], v[24:25] neg_lo:[0,1] neg_hi:[0,1]
	v_pk_add_f32 v[28:29], v[20:21], v[26:27]
	v_mov_b32_e32 v23, v20
	v_mov_b32_e32 v25, v29
	v_pk_add_f32 v[30:31], v[22:23], v[24:25] neg_lo:[0,1] neg_hi:[0,1]
	v_pk_add_f32 v[22:23], v[22:23], v[24:25]
	v_mov_b32_e32 v26, v27
	v_pk_add_f32 v[24:25], v[22:23], v[20:21] op_sel:[1,0] op_sel_hi:[0,1] neg_lo:[0,1] neg_hi:[0,1]
	v_pk_add_f32 v[32:33], v[28:29], v[24:25] op_sel_hi:[1,0] neg_lo:[0,1] neg_hi:[0,1]
	v_mov_b32_e32 v28, v29
	v_mov_b32_e32 v29, v23
	v_pk_mov_b32 v[24:25], v[20:21], v[24:25] op_sel:[1,0]
	v_mov_b32_e32 v27, v20
	v_pk_add_f32 v[24:25], v[28:29], v[24:25] neg_lo:[0,1] neg_hi:[0,1]
	v_mov_b32_e32 v32, v30
	v_pk_add_f32 v[20:21], v[26:27], v[24:25] neg_lo:[0,1] neg_hi:[0,1]
	v_mov_b32_e32 v31, v23
	v_pk_add_f32 v[24:25], v[32:33], v[20:21]
	v_readlane_b32 s9, v252, 20
	v_pk_add_f32 v[26:27], v[24:25], v[24:25] op_sel:[0,1] op_sel_hi:[1,0]
	s_nop 0
	v_pk_add_f32 v[22:23], v[22:23], v[26:27] op_sel:[1,0] op_sel_hi:[0,1]
	v_mov_b32_e32 v25, v22
	v_pk_add_f32 v[28:29], v[24:25], v[30:31] neg_lo:[0,1] neg_hi:[0,1]
	v_mov_b32_e32 v21, v26
	v_sub_f32_e32 v19, v24, v28
	v_pk_add_f32 v[20:21], v[20:21], v[28:29] neg_lo:[0,1] neg_hi:[0,1]
	v_sub_f32_e32 v19, v30, v19
	v_add_f32_e32 v19, v20, v19
	v_add_f32_e32 v19, v19, v21
	v_add_f32_e32 v19, v22, v19
	v_cndmask_b32_e32 v19, v236, v19, vcc
	v_cmp_ngt_f32_e32 vcc, -1.0, v18
	s_nop 1
	v_cndmask_b32_e32 v19, v237, v19, vcc
	v_cmp_neq_f32_e32 vcc, -1.0, v18
	s_nop 1
	v_cndmask_b32_e32 v19, v238, v19, vcc
	v_cmp_lt_f32_e64 vcc, |v18|, s12
	s_nop 1
	v_cndmask_b32_e32 v18, v19, v18, vcc
	v_sub_f32_e32 v18, v17, v18
	v_and_b32_e32 v17, 64, v220
	v_add_u32_e32 v19, -1, v220
	v_cmp_lt_i32_e32 vcc, v19, v17
	s_nop 1
	v_cndmask_b32_e32 v19, v19, v220, vcc
	v_lshlrev_b32_e32 v19, 2, v19
	ds_bpermute_b32 v20, v19, v16
	ds_bpermute_b32 v19, v19, v18
	s_waitcnt lgkmcnt(1)
; __device__ __forceinline__ void mlstm_gates_compute(LAS float* fl, const float (&gv)[4], const float* b_i, const float* b_f, int h, int tid) {
;     ...
;         for (int o = 1; o < 64; o <<= 1) { const float yf = __shfl_up(sf, o), yb = __shfl_up(sb, o); if (lane >= o) { sf += yf; sb += yb; } }
;         if (lane == 63) { wt[w * 2] = sf; wt[w * 2 + 1] = sb; }
	v_add_f32_e32 v20, v16, v20
	v_cndmask_b32_e64 v16, v20, v16, s[8:9]
	v_add_u32_e32 v20, -2, v220
	v_cmp_lt_i32_e32 vcc, v20, v17
	s_waitcnt lgkmcnt(0)
	v_add_f32_e32 v19, v18, v19
	v_cndmask_b32_e64 v19, v19, v18, s[8:9]
	v_cndmask_b32_e32 v20, v20, v220, vcc
	v_lshlrev_b32_e32 v20, 2, v20
	ds_bpermute_b32 v21, v20, v16
	ds_bpermute_b32 v20, v20, v19
	v_readlane_b32 s8, v252, 21
	v_readlane_b32 s9, v252, 22
	s_waitcnt lgkmcnt(1)
	v_add_f32_e32 v21, v16, v21
	s_waitcnt lgkmcnt(0)
	v_add_f32_e32 v20, v19, v20
	v_cndmask_b32_e64 v19, v20, v19, s[8:9]
	v_add_u32_e32 v20, -4, v220
	v_cmp_lt_i32_e32 vcc, v20, v17
	v_cndmask_b32_e64 v16, v21, v16, s[8:9]
	v_readlane_b32 s8, v252, 23
	v_cndmask_b32_e32 v20, v20, v220, vcc
	v_lshlrev_b32_e32 v20, 2, v20
	ds_bpermute_b32 v21, v20, v16
	ds_bpermute_b32 v20, v20, v19
	v_readlane_b32 s9, v252, 24
	s_waitcnt lgkmcnt(1)
	v_add_f32_e32 v21, v16, v21
	s_waitcnt lgkmcnt(0)
	v_add_f32_e32 v20, v19, v20
	v_cndmask_b32_e64 v19, v20, v19, s[8:9]
	v_add_u32_e32 v20, -8, v220
	v_cmp_lt_i32_e32 vcc, v20, v17
	v_cndmask_b32_e64 v16, v21, v16, s[8:9]
	v_readlane_b32 s8, v252, 25
	v_cndmask_b32_e32 v20, v20, v220, vcc
	v_lshlrev_b32_e32 v20, 2, v20
	ds_bpermute_b32 v21, v20, v16
	ds_bpermute_b32 v20, v20, v19
	v_readlane_b32 s9, v252, 26
	s_waitcnt lgkmcnt(1)
	v_add_f32_e32 v21, v16, v21
	s_waitcnt lgkmcnt(0)
	v_add_f32_e32 v20, v19, v20
	v_cndmask_b32_e64 v19, v20, v19, s[8:9]
	v_add_u32_e32 v20, -16, v220
	v_cmp_lt_i32_e32 vcc, v20, v17
	v_cndmask_b32_e64 v16, v21, v16, s[8:9]
	v_readlane_b32 s8, v252, 27
	v_cndmask_b32_e32 v20, v20, v220, vcc
	v_lshlrev_b32_e32 v20, 2, v20
	ds_bpermute_b32 v21, v20, v16
	ds_bpermute_b32 v20, v20, v19
	v_readlane_b32 s9, v252, 28
	s_waitcnt lgkmcnt(1)
	v_add_f32_e32 v21, v16, v21
	s_waitcnt lgkmcnt(0)
	v_add_f32_e32 v20, v19, v20
	v_cndmask_b32_e64 v19, v20, v19, s[8:9]
	v_cndmask_b32_e64 v20, v21, v16, s[8:9]
	v_subrev_u32_e32 v16, 32, v220
	v_cmp_lt_i32_e32 vcc, v16, v17
	s_nop 1
	v_cndmask_b32_e32 v16, v16, v220, vcc
	v_lshlrev_b32_e32 v16, 2, v16
	ds_bpermute_b32 v17, v16, v20
	ds_bpermute_b32 v21, v16, v19
	s_waitcnt lgkmcnt(1)
	v_add_f32_e32 v16, v20, v17
	s_waitcnt lgkmcnt(0)
	v_add_f32_e32 v17, v19, v21
	s_mov_b64 s[70:71], exec
	v_readlane_b32 s8, v252, 31
	v_readlane_b32 s9, v252, 32
	s_and_b64 s[8:9], s[70:71], s[8:9]
	s_mov_b64 exec, s[8:9]
	ds_write_b64 v155, v[16:17]
	s_or_b64 exec, exec, s[70:71]
	v_readlane_b32 s8, v252, 29
	v_readlane_b32 s9, v252, 30
	s_nop 1
	v_cndmask_b32_e64 v17, v17, v19, s[8:9]
	v_cndmask_b32_e64 v16, v16, v20, s[8:9]
